# g10: g8 + sc1 write-through on G3 HID stores (write-through publish strategy extended)
# speedup vs baseline: 1.0130x; 1.0130x over previous
; __device__ __forceinline__ unsigned cvt_pk_bf16(float lo, float hi) { unsigned r; asm volatile("v_cvt_pk_bf16_f32 %0, %1, %2" : "=v"(r) : "v"(lo), "v"(hi)); return r; }
;     __device__ __forceinline__ void operator()(const f32x4 (&acc)[2][2][4][2], const Unit& u, int wr, int wc, int fr, int fq) const {
;         const int row0 = u.pm * BM + wr * 64 + fr, col0 = u.pn * HALF + wc * 32 + 8 * fq;
; #pragma unroll
;         for (int ai = 0; ai < 2; ++ai)
; #pragma unroll
;             for (int m = 0; m < 4; ++m) { const int row = row0 + ai * HALF + m * 16;
;                 const float rs = rstd[row & 255];
;                 float h[8];
; #pragma unroll
;                 for (int n = 0; n < 2; ++n)
; #pragma unroll
;                     for (int e = 0; e < 4; ++e) { const float g = acc[ai][0][m][n][e] * rs, up = acc[ai][1][m][n][e] * rs;
;                         h[n * 4 + e] = g * up * __builtin_amdgcn_rcpf(1.f + __builtin_amdgcn_exp2f(-1.4426950408889634f * g)); }
;                 u32x4 w; w.x = cvt_pk_bf16(h[0], h[1]); w.y = cvt_pk_bf16(h[2], h[3]); w.z = cvt_pk_bf16(h[4], h[5]); w.w = cvt_pk_bf16(h[6], h[7]);
;                 *(u32x4*)(O + (size_t)row * ldc + col0) = w; }
.LBB0_371:
	ds_read_b32 v230, v142
	ds_read_b32 v231, v142 offset:64
	ds_read_b32 v232, v142 offset:128
	ds_read_b32 v233, v142 offset:192
	ds_read_b32 v234, v142 offset:512
	ds_read_b32 v235, v142 offset:576
	ds_read_b32 v236, v142 offset:640
	ds_read_b32 v237, v142 offset:704
	v_lshl_or_b32 v138, s76, 7, v143
	v_lshl_add_u32 v145, s77, 8, v140
	v_ashrrev_i32_e32 v139, 31, v138
	v_lshlrev_b64 v[238:239], 1, v[138:139]
	v_mov_b64_e32 v[240:241], s[4:5]
	v_mad_i64_i32 v[242:243], s[20:21], v145, s36, v[240:241]
	v_lshl_add_u64 v[242:243], v[242:243], 0, v[238:239]
	s_waitcnt lgkmcnt(0)
	v_mul_f32_e32 v124, v124, v230
	v_mul_f32_e32 v125, v125, v230
	v_mul_f32_e32 v126, v126, v230
	v_mul_f32_e32 v127, v127, v230
	v_mul_f32_e32 v116, v116, v230
	v_mul_f32_e32 v117, v117, v230
	v_mul_f32_e32 v118, v118, v230
	v_mul_f32_e32 v119, v119, v230
	v_mul_f32_e32 v120, v120, v230
	v_mul_f32_e32 v121, v121, v230
	v_mul_f32_e32 v122, v122, v230
	v_mul_f32_e32 v123, v123, v230
	v_mul_f32_e32 v112, v112, v230
	v_mul_f32_e32 v113, v113, v230
	v_mul_f32_e32 v114, v114, v230
	v_mul_f32_e32 v115, v115, v230
	v_mul_f32_e32 v214, 0xbfb8aa3b, v124
	v_mul_f32_e32 v215, 0xbfb8aa3b, v125
	v_mul_f32_e32 v216, 0xbfb8aa3b, v126
	v_mul_f32_e32 v217, 0xbfb8aa3b, v127
	v_mul_f32_e32 v218, 0xbfb8aa3b, v116
	v_mul_f32_e32 v219, 0xbfb8aa3b, v117
	v_mul_f32_e32 v220, 0xbfb8aa3b, v118
	v_mul_f32_e32 v221, 0xbfb8aa3b, v119
	v_exp_f32_e32 v214, v214
	v_exp_f32_e32 v215, v215
	v_exp_f32_e32 v216, v216
	v_exp_f32_e32 v217, v217
	v_exp_f32_e32 v218, v218
	v_exp_f32_e32 v219, v219
	v_exp_f32_e32 v220, v220
	v_exp_f32_e32 v221, v221
	v_mul_f32_e32 v120, v124, v120
	v_mul_f32_e32 v121, v125, v121
	v_mul_f32_e32 v122, v126, v122
	v_mul_f32_e32 v123, v127, v123
	v_mul_f32_e32 v112, v116, v112
	v_mul_f32_e32 v113, v117, v113
	v_mul_f32_e32 v114, v118, v114
	v_mul_f32_e32 v115, v119, v115
	v_add_f32_e32 v214, 1.0, v214
	v_add_f32_e32 v215, 1.0, v215
	v_add_f32_e32 v216, 1.0, v216
	v_add_f32_e32 v217, 1.0, v217
	v_add_f32_e32 v218, 1.0, v218
	v_add_f32_e32 v219, 1.0, v219
	v_add_f32_e32 v220, 1.0, v220
	v_add_f32_e32 v221, 1.0, v221
	v_rcp_f32_e32 v214, v214
	v_rcp_f32_e32 v215, v215
	v_rcp_f32_e32 v216, v216
	v_rcp_f32_e32 v217, v217
	v_rcp_f32_e32 v218, v218
	v_rcp_f32_e32 v219, v219
	v_rcp_f32_e32 v220, v220
	v_rcp_f32_e32 v221, v221
	v_mul_f32_e32 v124, v120, v214
	v_mul_f32_e32 v125, v121, v215
	v_mul_f32_e32 v126, v122, v216
	v_mul_f32_e32 v127, v123, v217
	v_mul_f32_e32 v116, v112, v218
	v_mul_f32_e32 v117, v113, v219
	v_mul_f32_e32 v118, v114, v220
	v_mul_f32_e32 v119, v115, v221
	v_cvt_pk_bf16_f32 v222, v124, v125
	v_cvt_pk_bf16_f32 v223, v126, v127
	v_cvt_pk_bf16_f32 v224, v116, v117
	v_cvt_pk_bf16_f32 v225, v118, v119
	global_store_dwordx4 v[242:243], v[222:225], off sc1
	v_mul_f32_e32 v108, v108, v231
	v_mul_f32_e32 v109, v109, v231
	v_mul_f32_e32 v110, v110, v231
	v_mul_f32_e32 v111, v111, v231
	v_mul_f32_e32 v100, v100, v231
	v_mul_f32_e32 v101, v101, v231
	v_mul_f32_e32 v102, v102, v231
	v_mul_f32_e32 v103, v103, v231
	v_mul_f32_e32 v104, v104, v231
	v_mul_f32_e32 v105, v105, v231
	v_mul_f32_e32 v106, v106, v231
	v_mul_f32_e32 v107, v107, v231
	v_mul_f32_e32 v96, v96, v231
	v_mul_f32_e32 v97, v97, v231
	v_mul_f32_e32 v98, v98, v231
	v_mul_f32_e32 v99, v99, v231
	v_mul_f32_e32 v214, 0xbfb8aa3b, v108
	v_mul_f32_e32 v215, 0xbfb8aa3b, v109
	v_mul_f32_e32 v216, 0xbfb8aa3b, v110
	v_mul_f32_e32 v217, 0xbfb8aa3b, v111
	v_mul_f32_e32 v218, 0xbfb8aa3b, v100
	v_mul_f32_e32 v219, 0xbfb8aa3b, v101
	v_mul_f32_e32 v220, 0xbfb8aa3b, v102
	v_mul_f32_e32 v221, 0xbfb8aa3b, v103
	v_exp_f32_e32 v214, v214
	v_exp_f32_e32 v215, v215
	v_exp_f32_e32 v216, v216
	v_exp_f32_e32 v217, v217
	v_exp_f32_e32 v218, v218
	v_exp_f32_e32 v219, v219
	v_exp_f32_e32 v220, v220
	v_exp_f32_e32 v221, v221
	v_mul_f32_e32 v104, v108, v104
	v_mul_f32_e32 v105, v109, v105
	v_mul_f32_e32 v106, v110, v106
	v_mul_f32_e32 v107, v111, v107
	v_mul_f32_e32 v96, v100, v96
	v_mul_f32_e32 v97, v101, v97
	v_mul_f32_e32 v98, v102, v98
	v_mul_f32_e32 v99, v103, v99
	v_add_f32_e32 v214, 1.0, v214
	v_add_f32_e32 v215, 1.0, v215
	v_add_f32_e32 v216, 1.0, v216
	v_add_f32_e32 v217, 1.0, v217
	v_add_f32_e32 v218, 1.0, v218
	v_add_f32_e32 v219, 1.0, v219
	v_add_f32_e32 v220, 1.0, v220
	v_add_f32_e32 v221, 1.0, v221
	v_rcp_f32_e32 v214, v214
	v_rcp_f32_e32 v215, v215
	v_rcp_f32_e32 v216, v216
	v_rcp_f32_e32 v217, v217
	v_rcp_f32_e32 v218, v218
	v_rcp_f32_e32 v219, v219
	v_rcp_f32_e32 v220, v220
	v_rcp_f32_e32 v221, v221
	v_mul_f32_e32 v108, v104, v214
	v_mul_f32_e32 v109, v105, v215
	v_mul_f32_e32 v110, v106, v216
	v_mul_f32_e32 v111, v107, v217
	v_mul_f32_e32 v100, v96, v218
	v_mul_f32_e32 v101, v97, v219
	v_mul_f32_e32 v102, v98, v220
	v_mul_f32_e32 v103, v99, v221
	v_cvt_pk_bf16_f32 v226, v108, v109
	v_cvt_pk_bf16_f32 v227, v110, v111
	v_cvt_pk_bf16_f32 v228, v100, v101
	v_cvt_pk_bf16_f32 v229, v102, v103
	s_mov_b64 s[20:21], 0x2c000
	v_lshl_add_u64 v[244:245], v[242:243], 0, s[20:21]
	global_store_dwordx4 v[244:245], v[226:229], off sc1
	v_mul_f32_e32 v92, v92, v232
	v_mul_f32_e32 v93, v93, v232
	v_mul_f32_e32 v94, v94, v232
	v_mul_f32_e32 v95, v95, v232
	v_mul_f32_e32 v84, v84, v232
	v_mul_f32_e32 v85, v85, v232
	v_mul_f32_e32 v86, v86, v232
	v_mul_f32_e32 v87, v87, v232
	v_mul_f32_e32 v88, v88, v232
	v_mul_f32_e32 v89, v89, v232
	v_mul_f32_e32 v90, v90, v232
	v_mul_f32_e32 v91, v91, v232
	v_mul_f32_e32 v80, v80, v232
	v_mul_f32_e32 v81, v81, v232
	v_mul_f32_e32 v82, v82, v232
	v_mul_f32_e32 v83, v83, v232
	v_mul_f32_e32 v214, 0xbfb8aa3b, v92
	v_mul_f32_e32 v215, 0xbfb8aa3b, v93
	v_mul_f32_e32 v216, 0xbfb8aa3b, v94
; __device__ __forceinline__ unsigned cvt_pk_bf16(float lo, float hi) { unsigned r; asm volatile("v_cvt_pk_bf16_f32 %0, %1, %2" : "=v"(r) : "v"(lo), "v"(hi)); return r; }
;     __device__ __forceinline__ void operator()(const f32x4 (&acc)[2][2][4][2], const Unit& u, int wr, int wc, int fr, int fq) const {
;     ...
;         for (int ai = 0; ai < 2; ++ai)
; #pragma unroll
;             for (int m = 0; m < 4; ++m) { const int row = row0 + ai * HALF + m * 16;
;                 const float rs = rstd[row & 255];
;                 float h[8];
; #pragma unroll
;                 for (int n = 0; n < 2; ++n)
; #pragma unroll
;                     for (int e = 0; e < 4; ++e) { const float g = acc[ai][0][m][n][e] * rs, up = acc[ai][1][m][n][e] * rs;
;                         h[n * 4 + e] = g * up * __builtin_amdgcn_rcpf(1.f + __builtin_amdgcn_exp2f(-1.4426950408889634f * g)); }
;                 u32x4 w; w.x = cvt_pk_bf16(h[0], h[1]); w.y = cvt_pk_bf16(h[2], h[3]); w.z = cvt_pk_bf16(h[4], h[5]); w.w = cvt_pk_bf16(h[6], h[7]);
;                 *(u32x4*)(O + (size_t)row * ldc + col0) = w; }
	v_mul_f32_e32 v217, 0xbfb8aa3b, v95
	v_mul_f32_e32 v218, 0xbfb8aa3b, v84
	v_mul_f32_e32 v219, 0xbfb8aa3b, v85
	v_mul_f32_e32 v220, 0xbfb8aa3b, v86
	v_mul_f32_e32 v221, 0xbfb8aa3b, v87
	v_exp_f32_e32 v214, v214
	v_exp_f32_e32 v215, v215
	v_exp_f32_e32 v216, v216
	v_exp_f32_e32 v217, v217
	v_exp_f32_e32 v218, v218
	v_exp_f32_e32 v219, v219
	v_exp_f32_e32 v220, v220
	v_exp_f32_e32 v221, v221
	v_mul_f32_e32 v88, v92, v88
	v_mul_f32_e32 v89, v93, v89
	v_mul_f32_e32 v90, v94, v90
	v_mul_f32_e32 v91, v95, v91
	v_mul_f32_e32 v80, v84, v80
	v_mul_f32_e32 v81, v85, v81
	v_mul_f32_e32 v82, v86, v82
	v_mul_f32_e32 v83, v87, v83
	v_add_f32_e32 v214, 1.0, v214
	v_add_f32_e32 v215, 1.0, v215
	v_add_f32_e32 v216, 1.0, v216
	v_add_f32_e32 v217, 1.0, v217
	v_add_f32_e32 v218, 1.0, v218
	v_add_f32_e32 v219, 1.0, v219
	v_add_f32_e32 v220, 1.0, v220
	v_add_f32_e32 v221, 1.0, v221
	v_rcp_f32_e32 v214, v214
	v_rcp_f32_e32 v215, v215
	v_rcp_f32_e32 v216, v216
	v_rcp_f32_e32 v217, v217
	v_rcp_f32_e32 v218, v218
	v_rcp_f32_e32 v219, v219
	v_rcp_f32_e32 v220, v220
	v_rcp_f32_e32 v221, v221
	v_mul_f32_e32 v92, v88, v214
	v_mul_f32_e32 v93, v89, v215
	v_mul_f32_e32 v94, v90, v216
	v_mul_f32_e32 v95, v91, v217
	v_mul_f32_e32 v84, v80, v218
	v_mul_f32_e32 v85, v81, v219
	v_mul_f32_e32 v86, v82, v220
	v_mul_f32_e32 v87, v83, v221
	v_cvt_pk_bf16_f32 v222, v92, v93
	v_cvt_pk_bf16_f32 v223, v94, v95
	v_cvt_pk_bf16_f32 v224, v84, v85
	v_cvt_pk_bf16_f32 v225, v86, v87
	s_mov_b64 s[20:21], 0x58000
	v_lshl_add_u64 v[244:245], v[242:243], 0, s[20:21]
	global_store_dwordx4 v[244:245], v[222:225], off sc1
	v_mul_f32_e32 v76, v76, v233
	v_mul_f32_e32 v77, v77, v233
	v_mul_f32_e32 v78, v78, v233
	v_mul_f32_e32 v79, v79, v233
	v_mul_f32_e32 v68, v68, v233
	v_mul_f32_e32 v69, v69, v233
	v_mul_f32_e32 v70, v70, v233
	v_mul_f32_e32 v71, v71, v233
	v_mul_f32_e32 v72, v72, v233
	v_mul_f32_e32 v73, v73, v233
	v_mul_f32_e32 v74, v74, v233
	v_mul_f32_e32 v75, v75, v233
	v_mul_f32_e32 v64, v64, v233
	v_mul_f32_e32 v65, v65, v233
	v_mul_f32_e32 v66, v66, v233
	v_mul_f32_e32 v67, v67, v233
	v_mul_f32_e32 v214, 0xbfb8aa3b, v76
	v_mul_f32_e32 v215, 0xbfb8aa3b, v77
	v_mul_f32_e32 v216, 0xbfb8aa3b, v78
	v_mul_f32_e32 v217, 0xbfb8aa3b, v79
	v_mul_f32_e32 v218, 0xbfb8aa3b, v68
	v_mul_f32_e32 v219, 0xbfb8aa3b, v69
	v_mul_f32_e32 v220, 0xbfb8aa3b, v70
	v_mul_f32_e32 v221, 0xbfb8aa3b, v71
	v_exp_f32_e32 v214, v214
	v_exp_f32_e32 v215, v215
	v_exp_f32_e32 v216, v216
	v_exp_f32_e32 v217, v217
	v_exp_f32_e32 v218, v218
	v_exp_f32_e32 v219, v219
	v_exp_f32_e32 v220, v220
	v_exp_f32_e32 v221, v221
	v_mul_f32_e32 v72, v76, v72
	v_mul_f32_e32 v73, v77, v73
	v_mul_f32_e32 v74, v78, v74
	v_mul_f32_e32 v75, v79, v75
	v_mul_f32_e32 v64, v68, v64
	v_mul_f32_e32 v65, v69, v65
	v_mul_f32_e32 v66, v70, v66
	v_mul_f32_e32 v67, v71, v67
	v_add_f32_e32 v214, 1.0, v214
	v_add_f32_e32 v215, 1.0, v215
	v_add_f32_e32 v216, 1.0, v216
	v_add_f32_e32 v217, 1.0, v217
	v_add_f32_e32 v218, 1.0, v218
	v_add_f32_e32 v219, 1.0, v219
	v_add_f32_e32 v220, 1.0, v220
	v_add_f32_e32 v221, 1.0, v221
	v_rcp_f32_e32 v214, v214
	v_rcp_f32_e32 v215, v215
	v_rcp_f32_e32 v216, v216
	v_rcp_f32_e32 v217, v217
	v_rcp_f32_e32 v218, v218
	v_rcp_f32_e32 v219, v219
	v_rcp_f32_e32 v220, v220
	v_rcp_f32_e32 v221, v221
	v_mul_f32_e32 v76, v72, v214
	v_mul_f32_e32 v77, v73, v215
	v_mul_f32_e32 v78, v74, v216
	v_mul_f32_e32 v79, v75, v217
	v_mul_f32_e32 v68, v64, v218
	v_mul_f32_e32 v69, v65, v219
	v_mul_f32_e32 v70, v66, v220
	v_mul_f32_e32 v71, v67, v221
	v_cvt_pk_bf16_f32 v226, v76, v77
	v_cvt_pk_bf16_f32 v227, v78, v79
	v_cvt_pk_bf16_f32 v228, v68, v69
	v_cvt_pk_bf16_f32 v229, v70, v71
	s_mov_b64 s[20:21], 0x84000
	v_lshl_add_u64 v[244:245], v[242:243], 0, s[20:21]
	global_store_dwordx4 v[244:245], v[226:229], off sc1
	v_mul_f32_e32 v60, v60, v234
	v_mul_f32_e32 v61, v61, v234
	v_mul_f32_e32 v62, v62, v234
	v_mul_f32_e32 v63, v63, v234
	v_mul_f32_e32 v52, v52, v234
	v_mul_f32_e32 v53, v53, v234
	v_mul_f32_e32 v54, v54, v234
	v_mul_f32_e32 v55, v55, v234
	v_mul_f32_e32 v56, v56, v234
	v_mul_f32_e32 v57, v57, v234
	v_mul_f32_e32 v58, v58, v234
	v_mul_f32_e32 v59, v59, v234
	v_mul_f32_e32 v48, v48, v234
	v_mul_f32_e32 v49, v49, v234
	v_mul_f32_e32 v50, v50, v234
	v_mul_f32_e32 v51, v51, v234
	v_mul_f32_e32 v214, 0xbfb8aa3b, v60
	v_mul_f32_e32 v215, 0xbfb8aa3b, v61
	v_mul_f32_e32 v216, 0xbfb8aa3b, v62
	v_mul_f32_e32 v217, 0xbfb8aa3b, v63
	v_mul_f32_e32 v218, 0xbfb8aa3b, v52
	v_mul_f32_e32 v219, 0xbfb8aa3b, v53
	v_mul_f32_e32 v220, 0xbfb8aa3b, v54
	v_mul_f32_e32 v221, 0xbfb8aa3b, v55
	v_exp_f32_e32 v214, v214
	v_exp_f32_e32 v215, v215
	v_exp_f32_e32 v216, v216
	v_exp_f32_e32 v217, v217
	v_exp_f32_e32 v218, v218
	v_exp_f32_e32 v219, v219
	v_exp_f32_e32 v220, v220
	v_exp_f32_e32 v221, v221
	v_mul_f32_e32 v56, v60, v56
	v_mul_f32_e32 v57, v61, v57
	v_mul_f32_e32 v58, v62, v58
	v_mul_f32_e32 v59, v63, v59
	v_mul_f32_e32 v48, v52, v48
	v_mul_f32_e32 v49, v53, v49
	v_mul_f32_e32 v50, v54, v50
	v_mul_f32_e32 v51, v55, v51
	v_add_f32_e32 v214, 1.0, v214
	v_add_f32_e32 v215, 1.0, v215
	v_add_f32_e32 v216, 1.0, v216
	v_add_f32_e32 v217, 1.0, v217
	v_add_f32_e32 v218, 1.0, v218
	v_add_f32_e32 v219, 1.0, v219
	v_add_f32_e32 v220, 1.0, v220
	v_add_f32_e32 v221, 1.0, v221
	v_rcp_f32_e32 v214, v214
	v_rcp_f32_e32 v215, v215
	v_rcp_f32_e32 v216, v216
	v_rcp_f32_e32 v217, v217
	v_rcp_f32_e32 v218, v218
	v_rcp_f32_e32 v219, v219
	v_rcp_f32_e32 v220, v220
	v_rcp_f32_e32 v221, v221
	v_mul_f32_e32 v60, v56, v214
	v_mul_f32_e32 v61, v57, v215
	v_mul_f32_e32 v62, v58, v216
	v_mul_f32_e32 v63, v59, v217
	v_mul_f32_e32 v52, v48, v218
	v_mul_f32_e32 v53, v49, v219
; __device__ __forceinline__ unsigned cvt_pk_bf16(float lo, float hi) { unsigned r; asm volatile("v_cvt_pk_bf16_f32 %0, %1, %2" : "=v"(r) : "v"(lo), "v"(hi)); return r; }
; #define PG8_BAR __builtin_amdgcn_s_barrier()
;     __device__ __forceinline__ void operator()(const f32x4 (&acc)[2][2][4][2], const Unit& u, int wr, int wc, int fr, int fq) const {
;     ...
;         for (int ai = 0; ai < 2; ++ai)
; #pragma unroll
;             for (int m = 0; m < 4; ++m) { const int row = row0 + ai * HALF + m * 16;
;                 const float rs = rstd[row & 255];
;                 float h[8];
; #pragma unroll
;                 for (int n = 0; n < 2; ++n)
; #pragma unroll
;                     for (int e = 0; e < 4; ++e) { const float g = acc[ai][0][m][n][e] * rs, up = acc[ai][1][m][n][e] * rs;
;                         h[n * 4 + e] = g * up * __builtin_amdgcn_rcpf(1.f + __builtin_amdgcn_exp2f(-1.4426950408889634f * g)); }
;                 u32x4 w; w.x = cvt_pk_bf16(h[0], h[1]); w.y = cvt_pk_bf16(h[2], h[3]); w.z = cvt_pk_bf16(h[4], h[5]); w.w = cvt_pk_bf16(h[6], h[7]);
;                 *(u32x4*)(O + (size_t)row * ldc + col0) = w; }
; template <class Epi, class Sched, bool ALIGN_EPI = false, bool SP2 = false>
; __device__ __forceinline__ void gemm_phase(PG8_LAS unsigned char* lds, const Gemm g, const Sched& S, const Epi& E) {
;     ...
;         if constexpr (ALIGN_EPI) { if (wr == 0) PG8_BAR; }
;         if constexpr (!Epi::AFTER_DRAIN) { E(acc, cur, wr, wc, fr, fq); S.done(cur); }
;         if (!has_next) break;
; #pragma unroll
;         for (int a = 0; a < 2; ++a)
; #pragma unroll
;             for (int b = 0; b < 2; ++b)
; #pragma unroll
;                 for (int m = 0; m < 4; ++m)
; #pragma unroll
;                     for (int n = 0; n < 2; ++n) acc[a][b][m][n] = (f32x4){0.f, 0.f, 0.f, 0.f};
;         cur = nxt; cA = nA; cB = nB; ++ui;
;         if constexpr (ALIGN_EPI) { if (wr == 1) PG8_BAR; }
	v_mul_f32_e32 v54, v50, v220
	v_mul_f32_e32 v55, v51, v221
	v_cvt_pk_bf16_f32 v222, v60, v61
	v_cvt_pk_bf16_f32 v223, v62, v63
	v_cvt_pk_bf16_f32 v224, v52, v53
	v_cvt_pk_bf16_f32 v225, v54, v55
	s_mov_b64 s[20:21], 0x160000
	v_lshl_add_u64 v[244:245], v[242:243], 0, s[20:21]
	global_store_dwordx4 v[244:245], v[222:225], off sc1
	v_mul_f32_e32 v44, v44, v235
	v_mul_f32_e32 v45, v45, v235
	v_mul_f32_e32 v46, v46, v235
	v_mul_f32_e32 v47, v47, v235
	v_mul_f32_e32 v36, v36, v235
	v_mul_f32_e32 v37, v37, v235
	v_mul_f32_e32 v38, v38, v235
	v_mul_f32_e32 v39, v39, v235
	v_mul_f32_e32 v40, v40, v235
	v_mul_f32_e32 v41, v41, v235
	v_mul_f32_e32 v42, v42, v235
	v_mul_f32_e32 v43, v43, v235
	v_mul_f32_e32 v32, v32, v235
	v_mul_f32_e32 v33, v33, v235
	v_mul_f32_e32 v34, v34, v235
	v_mul_f32_e32 v35, v35, v235
	v_mul_f32_e32 v214, 0xbfb8aa3b, v44
	v_mul_f32_e32 v215, 0xbfb8aa3b, v45
	v_mul_f32_e32 v216, 0xbfb8aa3b, v46
	v_mul_f32_e32 v217, 0xbfb8aa3b, v47
	v_mul_f32_e32 v218, 0xbfb8aa3b, v36
	v_mul_f32_e32 v219, 0xbfb8aa3b, v37
	v_mul_f32_e32 v220, 0xbfb8aa3b, v38
	v_mul_f32_e32 v221, 0xbfb8aa3b, v39
	v_exp_f32_e32 v214, v214
	v_exp_f32_e32 v215, v215
	v_exp_f32_e32 v216, v216
	v_exp_f32_e32 v217, v217
	v_exp_f32_e32 v218, v218
	v_exp_f32_e32 v219, v219
	v_exp_f32_e32 v220, v220
	v_exp_f32_e32 v221, v221
	v_mul_f32_e32 v40, v44, v40
	v_mul_f32_e32 v41, v45, v41
	v_mul_f32_e32 v42, v46, v42
	v_mul_f32_e32 v43, v47, v43
	v_mul_f32_e32 v32, v36, v32
	v_mul_f32_e32 v33, v37, v33
	v_mul_f32_e32 v34, v38, v34
	v_mul_f32_e32 v35, v39, v35
	v_add_f32_e32 v214, 1.0, v214
	v_add_f32_e32 v215, 1.0, v215
	v_add_f32_e32 v216, 1.0, v216
	v_add_f32_e32 v217, 1.0, v217
	v_add_f32_e32 v218, 1.0, v218
	v_add_f32_e32 v219, 1.0, v219
	v_add_f32_e32 v220, 1.0, v220
	v_add_f32_e32 v221, 1.0, v221
	v_rcp_f32_e32 v214, v214
	v_rcp_f32_e32 v215, v215
	v_rcp_f32_e32 v216, v216
	v_rcp_f32_e32 v217, v217
	v_rcp_f32_e32 v218, v218
	v_rcp_f32_e32 v219, v219
	v_rcp_f32_e32 v220, v220
	v_rcp_f32_e32 v221, v221
	v_mul_f32_e32 v44, v40, v214
	v_mul_f32_e32 v45, v41, v215
	v_mul_f32_e32 v46, v42, v216
	v_mul_f32_e32 v47, v43, v217
	v_mul_f32_e32 v36, v32, v218
	v_mul_f32_e32 v37, v33, v219
	v_mul_f32_e32 v38, v34, v220
	v_mul_f32_e32 v39, v35, v221
	v_cvt_pk_bf16_f32 v226, v44, v45
	v_cvt_pk_bf16_f32 v227, v46, v47
	v_cvt_pk_bf16_f32 v228, v36, v37
	v_cvt_pk_bf16_f32 v229, v38, v39
	s_mov_b64 s[20:21], 0x18c000
	v_lshl_add_u64 v[244:245], v[242:243], 0, s[20:21]
	global_store_dwordx4 v[244:245], v[226:229], off sc1
	v_mul_f32_e32 v28, v28, v236
	v_mul_f32_e32 v29, v29, v236
	v_mul_f32_e32 v30, v30, v236
	v_mul_f32_e32 v31, v31, v236
	v_mul_f32_e32 v20, v20, v236
	v_mul_f32_e32 v21, v21, v236
	v_mul_f32_e32 v22, v22, v236
	v_mul_f32_e32 v23, v23, v236
	v_mul_f32_e32 v24, v24, v236
	v_mul_f32_e32 v25, v25, v236
	v_mul_f32_e32 v26, v26, v236
	v_mul_f32_e32 v27, v27, v236
	v_mul_f32_e32 v16, v16, v236
	v_mul_f32_e32 v17, v17, v236
	v_mul_f32_e32 v18, v18, v236
	v_mul_f32_e32 v19, v19, v236
	v_mul_f32_e32 v214, 0xbfb8aa3b, v28
	v_mul_f32_e32 v215, 0xbfb8aa3b, v29
	v_mul_f32_e32 v216, 0xbfb8aa3b, v30
	v_mul_f32_e32 v217, 0xbfb8aa3b, v31
	v_mul_f32_e32 v218, 0xbfb8aa3b, v20
	v_mul_f32_e32 v219, 0xbfb8aa3b, v21
	v_mul_f32_e32 v220, 0xbfb8aa3b, v22
	v_mul_f32_e32 v221, 0xbfb8aa3b, v23
	v_exp_f32_e32 v214, v214
	v_exp_f32_e32 v215, v215
	v_exp_f32_e32 v216, v216
	v_exp_f32_e32 v217, v217
	v_exp_f32_e32 v218, v218
	v_exp_f32_e32 v219, v219
	v_exp_f32_e32 v220, v220
	v_exp_f32_e32 v221, v221
	v_mul_f32_e32 v24, v28, v24
	v_mul_f32_e32 v25, v29, v25
	v_mul_f32_e32 v26, v30, v26
	v_mul_f32_e32 v27, v31, v27
	v_mul_f32_e32 v16, v20, v16
	v_mul_f32_e32 v17, v21, v17
	v_mul_f32_e32 v18, v22, v18
	v_mul_f32_e32 v19, v23, v19
	v_add_f32_e32 v214, 1.0, v214
	v_add_f32_e32 v215, 1.0, v215
	v_add_f32_e32 v216, 1.0, v216
	v_add_f32_e32 v217, 1.0, v217
	v_add_f32_e32 v218, 1.0, v218
	v_add_f32_e32 v219, 1.0, v219
	v_add_f32_e32 v220, 1.0, v220
	v_add_f32_e32 v221, 1.0, v221
	v_rcp_f32_e32 v214, v214
	v_rcp_f32_e32 v215, v215
	v_rcp_f32_e32 v216, v216
	v_rcp_f32_e32 v217, v217
	v_rcp_f32_e32 v218, v218
	v_rcp_f32_e32 v219, v219
	v_rcp_f32_e32 v220, v220
	v_rcp_f32_e32 v221, v221
	v_mul_f32_e32 v28, v24, v214
	v_mul_f32_e32 v29, v25, v215
	v_mul_f32_e32 v30, v26, v216
	v_mul_f32_e32 v31, v27, v217
	v_mul_f32_e32 v20, v16, v218
	v_mul_f32_e32 v21, v17, v219
	v_mul_f32_e32 v22, v18, v220
	v_mul_f32_e32 v23, v19, v221
	v_cvt_pk_bf16_f32 v222, v28, v29
	v_cvt_pk_bf16_f32 v223, v30, v31
	v_cvt_pk_bf16_f32 v224, v20, v21
	v_cvt_pk_bf16_f32 v225, v22, v23
	s_mov_b64 s[20:21], 0x1b8000
	v_lshl_add_u64 v[244:245], v[242:243], 0, s[20:21]
	global_store_dwordx4 v[244:245], v[222:225], off sc1
	v_mul_f32_e32 v12, v12, v237
	v_mul_f32_e32 v13, v13, v237
	v_mul_f32_e32 v14, v14, v237
	v_mul_f32_e32 v15, v15, v237
	v_mul_f32_e32 v4, v4, v237
	v_mul_f32_e32 v5, v5, v237
	v_mul_f32_e32 v6, v6, v237
	v_mul_f32_e32 v7, v7, v237
	v_mul_f32_e32 v8, v8, v237
	v_mul_f32_e32 v9, v9, v237
	v_mul_f32_e32 v10, v10, v237
	v_mul_f32_e32 v11, v11, v237
	v_mul_f32_e32 v0, v0, v237
	v_mul_f32_e32 v1, v1, v237
	v_mul_f32_e32 v2, v2, v237
	v_mul_f32_e32 v3, v3, v237
	v_mul_f32_e32 v214, 0xbfb8aa3b, v12
	v_mul_f32_e32 v215, 0xbfb8aa3b, v13
	v_mul_f32_e32 v216, 0xbfb8aa3b, v14
	v_mul_f32_e32 v217, 0xbfb8aa3b, v15
	v_mul_f32_e32 v218, 0xbfb8aa3b, v4
	v_mul_f32_e32 v219, 0xbfb8aa3b, v5
	v_mul_f32_e32 v220, 0xbfb8aa3b, v6
	v_mul_f32_e32 v221, 0xbfb8aa3b, v7
	v_exp_f32_e32 v214, v214
	v_exp_f32_e32 v215, v215
	v_exp_f32_e32 v216, v216
	v_exp_f32_e32 v217, v217
	v_exp_f32_e32 v218, v218
	v_exp_f32_e32 v219, v219
	v_exp_f32_e32 v220, v220
	v_exp_f32_e32 v221, v221
	v_mul_f32_e32 v8, v12, v8
	v_mul_f32_e32 v9, v13, v9
	v_mul_f32_e32 v10, v14, v10
	v_mul_f32_e32 v11, v15, v11
	v_mul_f32_e32 v0, v4, v0
	v_mul_f32_e32 v1, v5, v1
	v_mul_f32_e32 v2, v6, v2
	v_mul_f32_e32 v3, v7, v3
	v_add_f32_e32 v214, 1.0, v214
	v_add_f32_e32 v215, 1.0, v215
	v_add_f32_e32 v216, 1.0, v216
	v_add_f32_e32 v217, 1.0, v217
	v_add_f32_e32 v218, 1.0, v218
	v_add_f32_e32 v219, 1.0, v219
	v_add_f32_e32 v220, 1.0, v220
	v_add_f32_e32 v221, 1.0, v221
	v_rcp_f32_e32 v214, v214
	v_rcp_f32_e32 v215, v215
	v_rcp_f32_e32 v216, v216
	v_rcp_f32_e32 v217, v217
	v_rcp_f32_e32 v218, v218
	v_rcp_f32_e32 v219, v219
	v_rcp_f32_e32 v220, v220
	v_rcp_f32_e32 v221, v221
	v_mul_f32_e32 v12, v8, v214
	v_mul_f32_e32 v13, v9, v215
	v_mul_f32_e32 v14, v10, v216
	v_mul_f32_e32 v15, v11, v217
	v_mul_f32_e32 v4, v0, v218
	v_mul_f32_e32 v5, v1, v219
	v_mul_f32_e32 v6, v2, v220
	v_mul_f32_e32 v7, v3, v221
	v_cvt_pk_bf16_f32 v226, v12, v13
	v_cvt_pk_bf16_f32 v227, v14, v15
	v_cvt_pk_bf16_f32 v228, v4, v5
	v_cvt_pk_bf16_f32 v229, v6, v7
	s_mov_b64 s[20:21], 0x1e4000
	v_lshl_add_u64 v[244:245], v[242:243], 0, s[20:21]
	global_store_dwordx4 v[244:245], v[226:229], off sc1
	s_mov_b64 s[20:21], -1
	s_andn2_b64 vcc, exec, s[42:43]
	s_cbranch_vccnz .LBB0_364
	s_andn2_b64 vcc, exec, s[44:45]
	s_cbranch_vccnz .LBB0_363
	s_barrier
	s_branch .LBB0_363
